# hyena filter generator (P0), last layer: the f32 VALU multiply-accumulate loop replaced by f32-operand matrix instructions v_mfma_f32_16x16x4_f32 (f32 in, f32 accumulate), latent filter units
# speedup vs baseline: 1.0227x; 1.0065x over previous
.LBB0_50:
	v_and_b32_e32 v34, 15, v170
	v_bfe_u32 v35, v170, 4, 2
	v_lshrrev_b32_e32 v36, 6, v170
	v_lshlrev_b32_e32 v37, 8, v34
	v_lshl_add_u32 v37, v35, 2, v37
	v_add_u32_e32 v37, 0x3210, v37
	ds_read_b32 v78, v37 offset:0
	ds_read_b32 v79, v37 offset:16
	ds_read_b32 v80, v37 offset:32
	ds_read_b32 v81, v37 offset:48
	ds_read_b32 v82, v37 offset:64
	ds_read_b32 v83, v37 offset:80
	ds_read_b32 v84, v37 offset:96
	ds_read_b32 v85, v37 offset:112
	ds_read_b32 v86, v37 offset:128
	ds_read_b32 v87, v37 offset:144
	ds_read_b32 v88, v37 offset:160
	ds_read_b32 v89, v37 offset:176
	ds_read_b32 v90, v37 offset:192
	ds_read_b32 v91, v37 offset:208
	ds_read_b32 v92, v37 offset:224
	ds_read_b32 v93, v37 offset:240
	ds_read_b32 v94, v37 offset:4096
	ds_read_b32 v95, v37 offset:4112
	ds_read_b32 v96, v37 offset:4128
	ds_read_b32 v97, v37 offset:4144
	ds_read_b32 v98, v37 offset:4160
	ds_read_b32 v99, v37 offset:4176
	ds_read_b32 v100, v37 offset:4192
	ds_read_b32 v101, v37 offset:4208
	ds_read_b32 v102, v37 offset:4224
	ds_read_b32 v103, v37 offset:4240
	ds_read_b32 v104, v37 offset:4256
	ds_read_b32 v105, v37 offset:4272
	ds_read_b32 v106, v37 offset:4288
	ds_read_b32 v107, v37 offset:4304
	ds_read_b32 v108, v37 offset:4320
	ds_read_b32 v109, v37 offset:4336
	v_readlane_b32 s76, v251, 42
	v_readlane_b32 s77, v251, 43
	v_readlane_b32 s80, v251, 46
	v_readlane_b32 s81, v251, 47
	v_lshl_add_u32 v38, v36, 7, v34
	v_lshlrev_b32_e32 v39, 12, v35
	v_lshl_add_u32 v39, v38, 2, v39
	v_lshlrev_b32_e32 v40, 15, v38
	v_lshl_add_u32 v40, v35, 4, v40
	v_lshlrev_b32_e32 v138, 2, v38
	v_lshlrev_b32_e32 v134, 2, v35
	v_add_u32_e32 v134, s20, v134
	v_add_u32_e32 v139, 0, v134
	v_cvt_f32_u32_e32 v139, v139
	v_mul_f32_e32 v126, 0xb9000000, v139
	v_add_u32_e32 v139, 1, v134
	v_cvt_f32_u32_e32 v139, v139
	v_mul_f32_e32 v127, 0xb9000000, v139
	v_add_u32_e32 v139, 2, v134
	v_cvt_f32_u32_e32 v139, v139
	v_mul_f32_e32 v128, 0xb9000000, v139
	v_add_u32_e32 v139, 3, v134
	v_cvt_f32_u32_e32 v139, v139
	v_mul_f32_e32 v129, 0xb9000000, v139
	v_add_u32_e32 v139, 16, v134
	v_cvt_f32_u32_e32 v139, v139
	v_mul_f32_e32 v130, 0xb9000000, v139
	v_add_u32_e32 v139, 17, v134
	v_cvt_f32_u32_e32 v139, v139
	v_mul_f32_e32 v131, 0xb9000000, v139
	v_add_u32_e32 v139, 18, v134
	v_cvt_f32_u32_e32 v139, v139
	v_mul_f32_e32 v132, 0xb9000000, v139
	v_add_u32_e32 v139, 19, v134
	v_cvt_f32_u32_e32 v139, v139
	v_mul_f32_e32 v133, 0xb9000000, v139
	v_and_b32_e32 v139, 63, v170
	v_xor_b32_e32 v135, 16, v139
	v_lshlrev_b32_e32 v135, 2, v135
	v_xor_b32_e32 v136, 32, v139
	v_lshlrev_b32_e32 v136, 2, v136
	v_cmp_lt_u32_e32 vcc, 3, v36
	v_cmp_eq_u32_e64 s[86:87], 0, v35
	s_and_b64 vcc, vcc, s[86:87]
	s_cmp_eq_u32 s20, 0
	s_cselect_b64 s[86:87], -1, 0
	s_and_b64 vcc, vcc, s[86:87]
	v_mov_b32_e32 v137, 1.0
	v_cndmask_b32_e32 v137, v137, v41, vcc
	s_waitcnt lgkmcnt(0)
	global_load_dword v140, v138, s[80:81] offset:0
	global_load_dword v141, v138, s[80:81] offset:64
	global_load_dword v142, v138, s[80:81] offset:128
	global_load_dword v143, v138, s[80:81] offset:192
	s_add_u32 s82, s76, 0x0
	s_addc_u32 s83, s77, 0
	global_load_dword v172, v39, s[82:83] offset:0
	global_load_dword v188, v39, s[82:83] offset:64
	global_load_dword v204, v39, s[82:83] offset:128
	global_load_dword v110, v39, s[82:83] offset:192
	s_add_u32 s82, s76, 0x4000
	s_addc_u32 s83, s77, 0
	global_load_dword v173, v39, s[82:83] offset:0
	global_load_dword v189, v39, s[82:83] offset:64
	global_load_dword v205, v39, s[82:83] offset:128
	global_load_dword v111, v39, s[82:83] offset:192
	s_add_u32 s82, s76, 0x8000
	s_addc_u32 s83, s77, 0
	global_load_dword v174, v39, s[82:83] offset:0
	global_load_dword v190, v39, s[82:83] offset:64
	global_load_dword v206, v39, s[82:83] offset:128
	global_load_dword v112, v39, s[82:83] offset:192
	s_add_u32 s82, s76, 0xc000
	s_addc_u32 s83, s77, 0
	global_load_dword v175, v39, s[82:83] offset:0
	global_load_dword v191, v39, s[82:83] offset:64
	global_load_dword v207, v39, s[82:83] offset:128
	global_load_dword v113, v39, s[82:83] offset:192
	s_add_u32 s82, s76, 0x10000
	s_addc_u32 s83, s77, 0
	global_load_dword v176, v39, s[82:83] offset:0
	global_load_dword v192, v39, s[82:83] offset:64
	global_load_dword v208, v39, s[82:83] offset:128
	global_load_dword v114, v39, s[82:83] offset:192
	s_add_u32 s82, s76, 0x14000
	s_addc_u32 s83, s77, 0
	global_load_dword v177, v39, s[82:83] offset:0
	global_load_dword v193, v39, s[82:83] offset:64
	global_load_dword v209, v39, s[82:83] offset:128
	global_load_dword v115, v39, s[82:83] offset:192
	s_add_u32 s82, s76, 0x18000
	s_addc_u32 s83, s77, 0
	global_load_dword v178, v39, s[82:83] offset:0
	global_load_dword v194, v39, s[82:83] offset:64
	global_load_dword v210, v39, s[82:83] offset:128
	global_load_dword v116, v39, s[82:83] offset:192
	s_add_u32 s82, s76, 0x1c000
	s_addc_u32 s83, s77, 0
	global_load_dword v179, v39, s[82:83] offset:0
	global_load_dword v195, v39, s[82:83] offset:64
	global_load_dword v211, v39, s[82:83] offset:128
	global_load_dword v117, v39, s[82:83] offset:192
	s_waitcnt vmcnt(28)
	v_mfma_f32_16x16x4_f32 v[2:5], v78, v172, 0
	v_mfma_f32_16x16x4_f32 v[6:9], v78, v188, 0
	v_mfma_f32_16x16x4_f32 v[10:13], v78, v204, 0
	v_mfma_f32_16x16x4_f32 v[14:17], v78, v110, 0
	v_mfma_f32_16x16x4_f32 v[18:21], v94, v172, 0
	v_mfma_f32_16x16x4_f32 v[22:25], v94, v188, 0
	v_mfma_f32_16x16x4_f32 v[26:29], v94, v204, 0
	v_mfma_f32_16x16x4_f32 v[30:33], v94, v110, 0
	s_add_u32 s82, s76, 0x20000
	s_addc_u32 s83, s77, 0
	global_load_dword v180, v39, s[82:83] offset:0
	global_load_dword v196, v39, s[82:83] offset:64
	global_load_dword v212, v39, s[82:83] offset:128
	global_load_dword v118, v39, s[82:83] offset:192
	s_waitcnt vmcnt(28)
	v_mfma_f32_16x16x4_f32 v[2:5], v79, v173, v[2:5]
	v_mfma_f32_16x16x4_f32 v[6:9], v79, v189, v[6:9]
	v_mfma_f32_16x16x4_f32 v[10:13], v79, v205, v[10:13]
	v_mfma_f32_16x16x4_f32 v[14:17], v79, v111, v[14:17]
	v_mfma_f32_16x16x4_f32 v[18:21], v95, v173, v[18:21]
	v_mfma_f32_16x16x4_f32 v[22:25], v95, v189, v[22:25]
	v_mfma_f32_16x16x4_f32 v[26:29], v95, v205, v[26:29]
	v_mfma_f32_16x16x4_f32 v[30:33], v95, v111, v[30:33]
	s_add_u32 s82, s76, 0x24000
	s_addc_u32 s83, s77, 0
	global_load_dword v181, v39, s[82:83] offset:0
	global_load_dword v197, v39, s[82:83] offset:64
	global_load_dword v213, v39, s[82:83] offset:128
	global_load_dword v119, v39, s[82:83] offset:192
	s_waitcnt vmcnt(28)
	v_mfma_f32_16x16x4_f32 v[2:5], v80, v174, v[2:5]
	v_mfma_f32_16x16x4_f32 v[6:9], v80, v190, v[6:9]
	v_mfma_f32_16x16x4_f32 v[10:13], v80, v206, v[10:13]
	v_mfma_f32_16x16x4_f32 v[14:17], v80, v112, v[14:17]
	v_mfma_f32_16x16x4_f32 v[18:21], v96, v174, v[18:21]
	v_mfma_f32_16x16x4_f32 v[22:25], v96, v190, v[22:25]
	v_mfma_f32_16x16x4_f32 v[26:29], v96, v206, v[26:29]
	v_mfma_f32_16x16x4_f32 v[30:33], v96, v112, v[30:33]
	s_add_u32 s82, s76, 0x28000
	s_addc_u32 s83, s77, 0
	global_load_dword v182, v39, s[82:83] offset:0
	global_load_dword v198, v39, s[82:83] offset:64
	global_load_dword v214, v39, s[82:83] offset:128
	global_load_dword v120, v39, s[82:83] offset:192
	s_waitcnt vmcnt(28)
	v_mfma_f32_16x16x4_f32 v[2:5], v81, v175, v[2:5]
	v_mfma_f32_16x16x4_f32 v[6:9], v81, v191, v[6:9]
	v_mfma_f32_16x16x4_f32 v[10:13], v81, v207, v[10:13]
	v_mfma_f32_16x16x4_f32 v[14:17], v81, v113, v[14:17]
	v_mfma_f32_16x16x4_f32 v[18:21], v97, v175, v[18:21]
	v_mfma_f32_16x16x4_f32 v[22:25], v97, v191, v[22:25]
	v_mfma_f32_16x16x4_f32 v[26:29], v97, v207, v[26:29]
	v_mfma_f32_16x16x4_f32 v[30:33], v97, v113, v[30:33]
	s_add_u32 s82, s76, 0x2c000
	s_addc_u32 s83, s77, 0
	global_load_dword v183, v39, s[82:83] offset:0
	global_load_dword v199, v39, s[82:83] offset:64
	global_load_dword v215, v39, s[82:83] offset:128
	global_load_dword v121, v39, s[82:83] offset:192
	s_waitcnt vmcnt(28)
	v_mfma_f32_16x16x4_f32 v[2:5], v82, v176, v[2:5]
	v_mfma_f32_16x16x4_f32 v[6:9], v82, v192, v[6:9]
	v_mfma_f32_16x16x4_f32 v[10:13], v82, v208, v[10:13]
	v_mfma_f32_16x16x4_f32 v[14:17], v82, v114, v[14:17]
	v_mfma_f32_16x16x4_f32 v[18:21], v98, v176, v[18:21]
	v_mfma_f32_16x16x4_f32 v[22:25], v98, v192, v[22:25]
	v_mfma_f32_16x16x4_f32 v[26:29], v98, v208, v[26:29]
	v_mfma_f32_16x16x4_f32 v[30:33], v98, v114, v[30:33]
	s_add_u32 s82, s76, 0x30000
	s_addc_u32 s83, s77, 0
	global_load_dword v184, v39, s[82:83] offset:0
	global_load_dword v200, v39, s[82:83] offset:64
	global_load_dword v216, v39, s[82:83] offset:128
	global_load_dword v122, v39, s[82:83] offset:192
	s_waitcnt vmcnt(28)
	v_mfma_f32_16x16x4_f32 v[2:5], v83, v177, v[2:5]
	v_mfma_f32_16x16x4_f32 v[6:9], v83, v193, v[6:9]
	v_mfma_f32_16x16x4_f32 v[10:13], v83, v209, v[10:13]
	v_mfma_f32_16x16x4_f32 v[14:17], v83, v115, v[14:17]
	v_mfma_f32_16x16x4_f32 v[18:21], v99, v177, v[18:21]
	v_mfma_f32_16x16x4_f32 v[22:25], v99, v193, v[22:25]
	v_mfma_f32_16x16x4_f32 v[26:29], v99, v209, v[26:29]
	v_mfma_f32_16x16x4_f32 v[30:33], v99, v115, v[30:33]
	s_add_u32 s82, s76, 0x34000
	s_addc_u32 s83, s77, 0
	global_load_dword v185, v39, s[82:83] offset:0
	global_load_dword v201, v39, s[82:83] offset:64
	global_load_dword v217, v39, s[82:83] offset:128
	global_load_dword v123, v39, s[82:83] offset:192
	s_waitcnt vmcnt(28)
	v_mfma_f32_16x16x4_f32 v[2:5], v84, v178, v[2:5]
	v_mfma_f32_16x16x4_f32 v[6:9], v84, v194, v[6:9]
	v_mfma_f32_16x16x4_f32 v[10:13], v84, v210, v[10:13]
	v_mfma_f32_16x16x4_f32 v[14:17], v84, v116, v[14:17]
	v_mfma_f32_16x16x4_f32 v[18:21], v100, v178, v[18:21]
	v_mfma_f32_16x16x4_f32 v[22:25], v100, v194, v[22:25]
	v_mfma_f32_16x16x4_f32 v[26:29], v100, v210, v[26:29]
	v_mfma_f32_16x16x4_f32 v[30:33], v100, v116, v[30:33]
	s_add_u32 s82, s76, 0x38000
	s_addc_u32 s83, s77, 0
	global_load_dword v186, v39, s[82:83] offset:0
	global_load_dword v202, v39, s[82:83] offset:64
	global_load_dword v218, v39, s[82:83] offset:128
	global_load_dword v124, v39, s[82:83] offset:192
	s_waitcnt vmcnt(28)
	v_mfma_f32_16x16x4_f32 v[2:5], v85, v179, v[2:5]
	v_mfma_f32_16x16x4_f32 v[6:9], v85, v195, v[6:9]
	v_mfma_f32_16x16x4_f32 v[10:13], v85, v211, v[10:13]
	v_mfma_f32_16x16x4_f32 v[14:17], v85, v117, v[14:17]
	v_mfma_f32_16x16x4_f32 v[18:21], v101, v179, v[18:21]
	v_mfma_f32_16x16x4_f32 v[22:25], v101, v195, v[22:25]
	v_mfma_f32_16x16x4_f32 v[26:29], v101, v211, v[26:29]
	v_mfma_f32_16x16x4_f32 v[30:33], v101, v117, v[30:33]
	s_add_u32 s82, s76, 0x3c000
	s_addc_u32 s83, s77, 0
	global_load_dword v187, v39, s[82:83] offset:0
	global_load_dword v203, v39, s[82:83] offset:64
	global_load_dword v219, v39, s[82:83] offset:128
	global_load_dword v125, v39, s[82:83] offset:192
	s_waitcnt vmcnt(28)
	v_mfma_f32_16x16x4_f32 v[2:5], v86, v180, v[2:5]
	v_mfma_f32_16x16x4_f32 v[6:9], v86, v196, v[6:9]
	v_mfma_f32_16x16x4_f32 v[10:13], v86, v212, v[10:13]
	v_mfma_f32_16x16x4_f32 v[14:17], v86, v118, v[14:17]
	v_mfma_f32_16x16x4_f32 v[18:21], v102, v180, v[18:21]
	v_mfma_f32_16x16x4_f32 v[22:25], v102, v196, v[22:25]
	v_mfma_f32_16x16x4_f32 v[26:29], v102, v212, v[26:29]
	v_mfma_f32_16x16x4_f32 v[30:33], v102, v118, v[30:33]
	s_waitcnt vmcnt(24)
	v_mfma_f32_16x16x4_f32 v[2:5], v87, v181, v[2:5]
	v_mfma_f32_16x16x4_f32 v[6:9], v87, v197, v[6:9]
	v_mfma_f32_16x16x4_f32 v[10:13], v87, v213, v[10:13]
	v_mfma_f32_16x16x4_f32 v[14:17], v87, v119, v[14:17]
	v_mfma_f32_16x16x4_f32 v[18:21], v103, v181, v[18:21]
	v_mfma_f32_16x16x4_f32 v[22:25], v103, v197, v[22:25]
	v_mfma_f32_16x16x4_f32 v[26:29], v103, v213, v[26:29]
	v_mfma_f32_16x16x4_f32 v[30:33], v103, v119, v[30:33]
	s_waitcnt vmcnt(20)
	v_mfma_f32_16x16x4_f32 v[2:5], v88, v182, v[2:5]
	v_mfma_f32_16x16x4_f32 v[6:9], v88, v198, v[6:9]
	v_mfma_f32_16x16x4_f32 v[10:13], v88, v214, v[10:13]
	v_mfma_f32_16x16x4_f32 v[14:17], v88, v120, v[14:17]
	v_mfma_f32_16x16x4_f32 v[18:21], v104, v182, v[18:21]
	v_mfma_f32_16x16x4_f32 v[22:25], v104, v198, v[22:25]
	v_mfma_f32_16x16x4_f32 v[26:29], v104, v214, v[26:29]
	v_mfma_f32_16x16x4_f32 v[30:33], v104, v120, v[30:33]
	s_waitcnt vmcnt(16)
	v_mfma_f32_16x16x4_f32 v[2:5], v89, v183, v[2:5]
	v_mfma_f32_16x16x4_f32 v[6:9], v89, v199, v[6:9]
	v_mfma_f32_16x16x4_f32 v[10:13], v89, v215, v[10:13]
	v_mfma_f32_16x16x4_f32 v[14:17], v89, v121, v[14:17]
	v_mfma_f32_16x16x4_f32 v[18:21], v105, v183, v[18:21]
	v_mfma_f32_16x16x4_f32 v[22:25], v105, v199, v[22:25]
	v_mfma_f32_16x16x4_f32 v[26:29], v105, v215, v[26:29]
	v_mfma_f32_16x16x4_f32 v[30:33], v105, v121, v[30:33]
	s_waitcnt vmcnt(12)
	v_mfma_f32_16x16x4_f32 v[2:5], v90, v184, v[2:5]
	v_mfma_f32_16x16x4_f32 v[6:9], v90, v200, v[6:9]
	v_mfma_f32_16x16x4_f32 v[10:13], v90, v216, v[10:13]
	v_mfma_f32_16x16x4_f32 v[14:17], v90, v122, v[14:17]
	v_mfma_f32_16x16x4_f32 v[18:21], v106, v184, v[18:21]
	v_mfma_f32_16x16x4_f32 v[22:25], v106, v200, v[22:25]
	v_mfma_f32_16x16x4_f32 v[26:29], v106, v216, v[26:29]
	v_mfma_f32_16x16x4_f32 v[30:33], v106, v122, v[30:33]
	s_waitcnt vmcnt(8)
	v_mfma_f32_16x16x4_f32 v[2:5], v91, v185, v[2:5]
	v_mfma_f32_16x16x4_f32 v[6:9], v91, v201, v[6:9]
	v_mfma_f32_16x16x4_f32 v[10:13], v91, v217, v[10:13]
	v_mfma_f32_16x16x4_f32 v[14:17], v91, v123, v[14:17]
	v_mfma_f32_16x16x4_f32 v[18:21], v107, v185, v[18:21]
	v_mfma_f32_16x16x4_f32 v[22:25], v107, v201, v[22:25]
	v_mfma_f32_16x16x4_f32 v[26:29], v107, v217, v[26:29]
	v_mfma_f32_16x16x4_f32 v[30:33], v107, v123, v[30:33]
	s_waitcnt vmcnt(4)
	v_mfma_f32_16x16x4_f32 v[2:5], v92, v186, v[2:5]
	v_mfma_f32_16x16x4_f32 v[6:9], v92, v202, v[6:9]
	v_mfma_f32_16x16x4_f32 v[10:13], v92, v218, v[10:13]
	v_mfma_f32_16x16x4_f32 v[14:17], v92, v124, v[14:17]
	v_mfma_f32_16x16x4_f32 v[18:21], v108, v186, v[18:21]
	v_mfma_f32_16x16x4_f32 v[22:25], v108, v202, v[22:25]
	v_mfma_f32_16x16x4_f32 v[26:29], v108, v218, v[26:29]
	v_mfma_f32_16x16x4_f32 v[30:33], v108, v124, v[30:33]
	s_waitcnt vmcnt(0)
	v_mfma_f32_16x16x4_f32 v[2:5], v93, v187, v[2:5]
	v_mfma_f32_16x16x4_f32 v[6:9], v93, v203, v[6:9]
	v_mfma_f32_16x16x4_f32 v[10:13], v93, v219, v[10:13]
	v_mfma_f32_16x16x4_f32 v[14:17], v93, v125, v[14:17]
	v_mfma_f32_16x16x4_f32 v[18:21], v109, v187, v[18:21]
	v_mfma_f32_16x16x4_f32 v[22:25], v109, v203, v[22:25]
	v_mfma_f32_16x16x4_f32 v[26:29], v109, v219, v[26:29]
	v_mfma_f32_16x16x4_f32 v[30:33], v109, v125, v[30:33]
	s_nop 7
	s_nop 7
	s_nop 3
	v_mul_f32_e64 v148, |v140|, v126
	v_mul_f32_e64 v149, |v140|, v127
	v_mul_f32_e64 v150, |v140|, v128
	v_mul_f32_e64 v151, |v140|, v129
	v_mul_f32_e64 v152, |v140|, v130
	v_mul_f32_e64 v153, |v140|, v131
	v_mul_f32_e64 v154, |v140|, v132
	v_mul_f32_e64 v155, |v140|, v133
	v_mul_f32_e32 v148, 0x3fb8aa3b, v148
	v_mul_f32_e32 v149, 0x3fb8aa3b, v149
	v_mul_f32_e32 v150, 0x3fb8aa3b, v150
	v_mul_f32_e32 v151, 0x3fb8aa3b, v151
	v_mul_f32_e32 v152, 0x3fb8aa3b, v152
	v_mul_f32_e32 v153, 0x3fb8aa3b, v153
	v_mul_f32_e32 v154, 0x3fb8aa3b, v154
	v_mul_f32_e32 v155, 0x3fb8aa3b, v155
	v_exp_f32_e32 v148, v148
	v_exp_f32_e32 v149, v149
	v_exp_f32_e32 v150, v150
	v_exp_f32_e32 v151, v151
	v_exp_f32_e32 v152, v152
	v_exp_f32_e32 v153, v153
	v_exp_f32_e32 v154, v154
	v_exp_f32_e32 v155, v155
	v_mul_f32_e32 v2, v148, v2
	v_mul_f32_e32 v3, v149, v3
	v_mul_f32_e32 v4, v150, v4
	v_mul_f32_e32 v5, v151, v5
	v_mul_f32_e32 v18, v152, v18
	v_mul_f32_e32 v19, v153, v19
	v_mul_f32_e32 v20, v154, v20
	v_mul_f32_e32 v21, v155, v21
	v_mul_f32_e32 v144, v2, v2
	v_mul_f32_e32 v144, v137, v144
	v_fmac_f32_e32 v144, v3, v3
	v_fmac_f32_e32 v144, v4, v4
	v_fmac_f32_e32 v144, v5, v5
	v_fmac_f32_e32 v144, v18, v18
	v_fmac_f32_e32 v144, v19, v19
	v_fmac_f32_e32 v144, v20, v20
	v_fmac_f32_e32 v144, v21, v21
	s_add_u32 s84, s40, 0x0
	s_addc_u32 s85, s41, 0
	global_store_dwordx4 v40, v[2:5], s[84:85]
	global_store_dwordx4 v40, v[18:21], s[84:85] offset:64
	v_mul_f32_e64 v148, |v141|, v126
	v_mul_f32_e64 v149, |v141|, v127
	v_mul_f32_e64 v150, |v141|, v128
	v_mul_f32_e64 v151, |v141|, v129
	v_mul_f32_e64 v152, |v141|, v130
	v_mul_f32_e64 v153, |v141|, v131
	v_mul_f32_e64 v154, |v141|, v132
	v_mul_f32_e64 v155, |v141|, v133
	v_mul_f32_e32 v148, 0x3fb8aa3b, v148
	v_mul_f32_e32 v149, 0x3fb8aa3b, v149
	v_mul_f32_e32 v150, 0x3fb8aa3b, v150
	v_mul_f32_e32 v151, 0x3fb8aa3b, v151
	v_mul_f32_e32 v152, 0x3fb8aa3b, v152
	v_mul_f32_e32 v153, 0x3fb8aa3b, v153
	v_mul_f32_e32 v154, 0x3fb8aa3b, v154
	v_mul_f32_e32 v155, 0x3fb8aa3b, v155
	v_exp_f32_e32 v148, v148
	v_exp_f32_e32 v149, v149
	v_exp_f32_e32 v150, v150
	v_exp_f32_e32 v151, v151
	v_exp_f32_e32 v152, v152
	v_exp_f32_e32 v153, v153
	v_exp_f32_e32 v154, v154
	v_exp_f32_e32 v155, v155
	v_mul_f32_e32 v6, v148, v6
	v_mul_f32_e32 v7, v149, v7
	v_mul_f32_e32 v8, v150, v8
	v_mul_f32_e32 v9, v151, v9
	v_mul_f32_e32 v22, v152, v22
	v_mul_f32_e32 v23, v153, v23
	v_mul_f32_e32 v24, v154, v24
	v_mul_f32_e32 v25, v155, v25
	v_mul_f32_e32 v145, v6, v6
	v_mul_f32_e32 v145, v137, v145
	v_fmac_f32_e32 v145, v7, v7
	v_fmac_f32_e32 v145, v8, v8
	v_fmac_f32_e32 v145, v9, v9
	v_fmac_f32_e32 v145, v22, v22
	v_fmac_f32_e32 v145, v23, v23
	v_fmac_f32_e32 v145, v24, v24
	v_fmac_f32_e32 v145, v25, v25
	s_add_u32 s84, s40, 0x80000
	s_addc_u32 s85, s41, 0
	global_store_dwordx4 v40, v[6:9], s[84:85]
	global_store_dwordx4 v40, v[22:25], s[84:85] offset:64
	v_mul_f32_e64 v148, |v142|, v126
	v_mul_f32_e64 v149, |v142|, v127
	v_mul_f32_e64 v150, |v142|, v128
	v_mul_f32_e64 v151, |v142|, v129
	v_mul_f32_e64 v152, |v142|, v130
	v_mul_f32_e64 v153, |v142|, v131
	v_mul_f32_e64 v154, |v142|, v132
	v_mul_f32_e64 v155, |v142|, v133
	v_mul_f32_e32 v148, 0x3fb8aa3b, v148
	v_mul_f32_e32 v149, 0x3fb8aa3b, v149
	v_mul_f32_e32 v150, 0x3fb8aa3b, v150
	v_mul_f32_e32 v151, 0x3fb8aa3b, v151
	v_mul_f32_e32 v152, 0x3fb8aa3b, v152
	v_mul_f32_e32 v153, 0x3fb8aa3b, v153
	v_mul_f32_e32 v154, 0x3fb8aa3b, v154
	v_mul_f32_e32 v155, 0x3fb8aa3b, v155
	v_exp_f32_e32 v148, v148
	v_exp_f32_e32 v149, v149
	v_exp_f32_e32 v150, v150
	v_exp_f32_e32 v151, v151
	v_exp_f32_e32 v152, v152
	v_exp_f32_e32 v153, v153
	v_exp_f32_e32 v154, v154
	v_exp_f32_e32 v155, v155
	v_mul_f32_e32 v10, v148, v10
	v_mul_f32_e32 v11, v149, v11
	v_mul_f32_e32 v12, v150, v12
	v_mul_f32_e32 v13, v151, v13
	v_mul_f32_e32 v26, v152, v26
	v_mul_f32_e32 v27, v153, v27
	v_mul_f32_e32 v28, v154, v28
	v_mul_f32_e32 v29, v155, v29
	v_mul_f32_e32 v146, v10, v10
	v_mul_f32_e32 v146, v137, v146
	v_fmac_f32_e32 v146, v11, v11
	v_fmac_f32_e32 v146, v12, v12
	v_fmac_f32_e32 v146, v13, v13
	v_fmac_f32_e32 v146, v26, v26
	v_fmac_f32_e32 v146, v27, v27
	v_fmac_f32_e32 v146, v28, v28
	v_fmac_f32_e32 v146, v29, v29
	s_add_u32 s84, s40, 0x100000
	s_addc_u32 s85, s41, 0
	global_store_dwordx4 v40, v[10:13], s[84:85]
	global_store_dwordx4 v40, v[26:29], s[84:85] offset:64
	v_mul_f32_e64 v148, |v143|, v126
	v_mul_f32_e64 v149, |v143|, v127
	v_mul_f32_e64 v150, |v143|, v128
	v_mul_f32_e64 v151, |v143|, v129
	v_mul_f32_e64 v152, |v143|, v130
	v_mul_f32_e64 v153, |v143|, v131
	v_mul_f32_e64 v154, |v143|, v132
	v_mul_f32_e64 v155, |v143|, v133
	v_mul_f32_e32 v148, 0x3fb8aa3b, v148
	v_mul_f32_e32 v149, 0x3fb8aa3b, v149
	v_mul_f32_e32 v150, 0x3fb8aa3b, v150
	v_mul_f32_e32 v151, 0x3fb8aa3b, v151
	v_mul_f32_e32 v152, 0x3fb8aa3b, v152
	v_mul_f32_e32 v153, 0x3fb8aa3b, v153
	v_mul_f32_e32 v154, 0x3fb8aa3b, v154
	v_mul_f32_e32 v155, 0x3fb8aa3b, v155
	v_exp_f32_e32 v148, v148
	v_exp_f32_e32 v149, v149
	v_exp_f32_e32 v150, v150
	v_exp_f32_e32 v151, v151
	v_exp_f32_e32 v152, v152
	v_exp_f32_e32 v153, v153
	v_exp_f32_e32 v154, v154
	v_exp_f32_e32 v155, v155
	v_mul_f32_e32 v14, v148, v14
	v_mul_f32_e32 v15, v149, v15
	v_mul_f32_e32 v16, v150, v16
	v_mul_f32_e32 v17, v151, v17
	v_mul_f32_e32 v30, v152, v30
	v_mul_f32_e32 v31, v153, v31
	v_mul_f32_e32 v32, v154, v32
	v_mul_f32_e32 v33, v155, v33
	v_mul_f32_e32 v147, v14, v14
	v_mul_f32_e32 v147, v137, v147
	v_fmac_f32_e32 v147, v15, v15
	v_fmac_f32_e32 v147, v16, v16
	v_fmac_f32_e32 v147, v17, v17
	v_fmac_f32_e32 v147, v30, v30
	v_fmac_f32_e32 v147, v31, v31
	v_fmac_f32_e32 v147, v32, v32
	v_fmac_f32_e32 v147, v33, v33
	s_add_u32 s84, s40, 0x180000
	s_addc_u32 s85, s41, 0
	global_store_dwordx4 v40, v[14:17], s[84:85]
	global_store_dwordx4 v40, v[30:33], s[84:85] offset:64
	ds_bpermute_b32 v148, v135, v144
	ds_bpermute_b32 v149, v135, v145
	ds_bpermute_b32 v150, v135, v146
	ds_bpermute_b32 v151, v135, v147
	s_waitcnt lgkmcnt(0)
	v_add_f32_e32 v144, v144, v148
	v_add_f32_e32 v145, v145, v149
	v_add_f32_e32 v146, v146, v150
	v_add_f32_e32 v147, v147, v151
	ds_bpermute_b32 v148, v136, v144
	ds_bpermute_b32 v149, v136, v145
	ds_bpermute_b32 v150, v136, v146
	ds_bpermute_b32 v151, v136, v147
	s_waitcnt lgkmcnt(0)
	v_add_f32_e32 v144, v144, v148
	v_add_f32_e32 v145, v145, v149
	v_add_f32_e32 v146, v146, v150
	v_add_f32_e32 v147, v147, v151
	global_store_dword v138, v144, s[26:27] offset:0
	global_store_dword v138, v145, s[26:27] offset:64
	global_store_dword v138, v146, s[26:27] offset:128
	global_store_dword v138, v147, s[26:27] offset:192
	s_nop 1
	global_load_dword v140, v138, s[80:81] offset:256
	global_load_dword v141, v138, s[80:81] offset:320
	global_load_dword v142, v138, s[80:81] offset:384
	global_load_dword v143, v138, s[80:81] offset:448
	s_add_u32 s82, s76, 0x100
	s_addc_u32 s83, s77, 0
	global_load_dword v172, v39, s[82:83] offset:0
	global_load_dword v188, v39, s[82:83] offset:64
	global_load_dword v204, v39, s[82:83] offset:128
	global_load_dword v110, v39, s[82:83] offset:192
	s_add_u32 s82, s76, 0x4100
	s_addc_u32 s83, s77, 0
	global_load_dword v173, v39, s[82:83] offset:0
	global_load_dword v189, v39, s[82:83] offset:64
	global_load_dword v205, v39, s[82:83] offset:128
	global_load_dword v111, v39, s[82:83] offset:192
	s_add_u32 s82, s76, 0x8100
	s_addc_u32 s83, s77, 0
	global_load_dword v174, v39, s[82:83] offset:0
	global_load_dword v190, v39, s[82:83] offset:64
	global_load_dword v206, v39, s[82:83] offset:128
	global_load_dword v112, v39, s[82:83] offset:192
	s_add_u32 s82, s76, 0xc100
	s_addc_u32 s83, s77, 0
	global_load_dword v175, v39, s[82:83] offset:0
	global_load_dword v191, v39, s[82:83] offset:64
	global_load_dword v207, v39, s[82:83] offset:128
	global_load_dword v113, v39, s[82:83] offset:192
	s_add_u32 s82, s76, 0x10100
	s_addc_u32 s83, s77, 0
	global_load_dword v176, v39, s[82:83] offset:0
	global_load_dword v192, v39, s[82:83] offset:64
	global_load_dword v208, v39, s[82:83] offset:128
	global_load_dword v114, v39, s[82:83] offset:192
	s_add_u32 s82, s76, 0x14100
	s_addc_u32 s83, s77, 0
	global_load_dword v177, v39, s[82:83] offset:0
	global_load_dword v193, v39, s[82:83] offset:64
	global_load_dword v209, v39, s[82:83] offset:128
	global_load_dword v115, v39, s[82:83] offset:192
	s_add_u32 s82, s76, 0x18100
	s_addc_u32 s83, s77, 0
	global_load_dword v178, v39, s[82:83] offset:0
	global_load_dword v194, v39, s[82:83] offset:64
	global_load_dword v210, v39, s[82:83] offset:128
	global_load_dword v116, v39, s[82:83] offset:192
	s_add_u32 s82, s76, 0x1c100
	s_addc_u32 s83, s77, 0
	global_load_dword v179, v39, s[82:83] offset:0
	global_load_dword v195, v39, s[82:83] offset:64
	global_load_dword v211, v39, s[82:83] offset:128
	global_load_dword v117, v39, s[82:83] offset:192
	s_waitcnt vmcnt(28)
	v_mfma_f32_16x16x4_f32 v[2:5], v78, v172, 0
	v_mfma_f32_16x16x4_f32 v[6:9], v78, v188, 0
	v_mfma_f32_16x16x4_f32 v[10:13], v78, v204, 0
	v_mfma_f32_16x16x4_f32 v[14:17], v78, v110, 0
	v_mfma_f32_16x16x4_f32 v[18:21], v94, v172, 0
	v_mfma_f32_16x16x4_f32 v[22:25], v94, v188, 0
	v_mfma_f32_16x16x4_f32 v[26:29], v94, v204, 0
	v_mfma_f32_16x16x4_f32 v[30:33], v94, v110, 0
	s_add_u32 s82, s76, 0x20100
	s_addc_u32 s83, s77, 0
	global_load_dword v180, v39, s[82:83] offset:0
	global_load_dword v196, v39, s[82:83] offset:64
	global_load_dword v212, v39, s[82:83] offset:128
	global_load_dword v118, v39, s[82:83] offset:192
	s_waitcnt vmcnt(28)
	v_mfma_f32_16x16x4_f32 v[2:5], v79, v173, v[2:5]
	v_mfma_f32_16x16x4_f32 v[6:9], v79, v189, v[6:9]
	v_mfma_f32_16x16x4_f32 v[10:13], v79, v205, v[10:13]
	v_mfma_f32_16x16x4_f32 v[14:17], v79, v111, v[14:17]
	v_mfma_f32_16x16x4_f32 v[18:21], v95, v173, v[18:21]
	v_mfma_f32_16x16x4_f32 v[22:25], v95, v189, v[22:25]
	v_mfma_f32_16x16x4_f32 v[26:29], v95, v205, v[26:29]
	v_mfma_f32_16x16x4_f32 v[30:33], v95, v111, v[30:33]
	s_add_u32 s82, s76, 0x24100
	s_addc_u32 s83, s77, 0
	global_load_dword v181, v39, s[82:83] offset:0
	global_load_dword v197, v39, s[82:83] offset:64
	global_load_dword v213, v39, s[82:83] offset:128
	global_load_dword v119, v39, s[82:83] offset:192
	s_waitcnt vmcnt(28)
	v_mfma_f32_16x16x4_f32 v[2:5], v80, v174, v[2:5]
	v_mfma_f32_16x16x4_f32 v[6:9], v80, v190, v[6:9]
	v_mfma_f32_16x16x4_f32 v[10:13], v80, v206, v[10:13]
	v_mfma_f32_16x16x4_f32 v[14:17], v80, v112, v[14:17]
	v_mfma_f32_16x16x4_f32 v[18:21], v96, v174, v[18:21]
	v_mfma_f32_16x16x4_f32 v[22:25], v96, v190, v[22:25]
	v_mfma_f32_16x16x4_f32 v[26:29], v96, v206, v[26:29]
	v_mfma_f32_16x16x4_f32 v[30:33], v96, v112, v[30:33]
	s_add_u32 s82, s76, 0x28100
	s_addc_u32 s83, s77, 0
	global_load_dword v182, v39, s[82:83] offset:0
	global_load_dword v198, v39, s[82:83] offset:64
	global_load_dword v214, v39, s[82:83] offset:128
	global_load_dword v120, v39, s[82:83] offset:192
	s_waitcnt vmcnt(28)
	v_mfma_f32_16x16x4_f32 v[2:5], v81, v175, v[2:5]
	v_mfma_f32_16x16x4_f32 v[6:9], v81, v191, v[6:9]
	v_mfma_f32_16x16x4_f32 v[10:13], v81, v207, v[10:13]
	v_mfma_f32_16x16x4_f32 v[14:17], v81, v113, v[14:17]
	v_mfma_f32_16x16x4_f32 v[18:21], v97, v175, v[18:21]
	v_mfma_f32_16x16x4_f32 v[22:25], v97, v191, v[22:25]
	v_mfma_f32_16x16x4_f32 v[26:29], v97, v207, v[26:29]
	v_mfma_f32_16x16x4_f32 v[30:33], v97, v113, v[30:33]
	s_add_u32 s82, s76, 0x2c100
	s_addc_u32 s83, s77, 0
	global_load_dword v183, v39, s[82:83] offset:0
	global_load_dword v199, v39, s[82:83] offset:64
	global_load_dword v215, v39, s[82:83] offset:128
	global_load_dword v121, v39, s[82:83] offset:192
	s_waitcnt vmcnt(28)
	v_mfma_f32_16x16x4_f32 v[2:5], v82, v176, v[2:5]
	v_mfma_f32_16x16x4_f32 v[6:9], v82, v192, v[6:9]
	v_mfma_f32_16x16x4_f32 v[10:13], v82, v208, v[10:13]
	v_mfma_f32_16x16x4_f32 v[14:17], v82, v114, v[14:17]
	v_mfma_f32_16x16x4_f32 v[18:21], v98, v176, v[18:21]
	v_mfma_f32_16x16x4_f32 v[22:25], v98, v192, v[22:25]
	v_mfma_f32_16x16x4_f32 v[26:29], v98, v208, v[26:29]
	v_mfma_f32_16x16x4_f32 v[30:33], v98, v114, v[30:33]
	s_add_u32 s82, s76, 0x30100
	s_addc_u32 s83, s77, 0
	global_load_dword v184, v39, s[82:83] offset:0
	global_load_dword v200, v39, s[82:83] offset:64
	global_load_dword v216, v39, s[82:83] offset:128
	global_load_dword v122, v39, s[82:83] offset:192
	s_waitcnt vmcnt(28)
	v_mfma_f32_16x16x4_f32 v[2:5], v83, v177, v[2:5]
	v_mfma_f32_16x16x4_f32 v[6:9], v83, v193, v[6:9]
	v_mfma_f32_16x16x4_f32 v[10:13], v83, v209, v[10:13]
	v_mfma_f32_16x16x4_f32 v[14:17], v83, v115, v[14:17]
	v_mfma_f32_16x16x4_f32 v[18:21], v99, v177, v[18:21]
	v_mfma_f32_16x16x4_f32 v[22:25], v99, v193, v[22:25]
	v_mfma_f32_16x16x4_f32 v[26:29], v99, v209, v[26:29]
	v_mfma_f32_16x16x4_f32 v[30:33], v99, v115, v[30:33]
	s_add_u32 s82, s76, 0x34100
	s_addc_u32 s83, s77, 0
	global_load_dword v185, v39, s[82:83] offset:0
	global_load_dword v201, v39, s[82:83] offset:64
	global_load_dword v217, v39, s[82:83] offset:128
	global_load_dword v123, v39, s[82:83] offset:192
	s_waitcnt vmcnt(28)
	v_mfma_f32_16x16x4_f32 v[2:5], v84, v178, v[2:5]
	v_mfma_f32_16x16x4_f32 v[6:9], v84, v194, v[6:9]
	v_mfma_f32_16x16x4_f32 v[10:13], v84, v210, v[10:13]
	v_mfma_f32_16x16x4_f32 v[14:17], v84, v116, v[14:17]
	v_mfma_f32_16x16x4_f32 v[18:21], v100, v178, v[18:21]
	v_mfma_f32_16x16x4_f32 v[22:25], v100, v194, v[22:25]
	v_mfma_f32_16x16x4_f32 v[26:29], v100, v210, v[26:29]
	v_mfma_f32_16x16x4_f32 v[30:33], v100, v116, v[30:33]
	s_add_u32 s82, s76, 0x38100
	s_addc_u32 s83, s77, 0
	global_load_dword v186, v39, s[82:83] offset:0
	global_load_dword v202, v39, s[82:83] offset:64
	global_load_dword v218, v39, s[82:83] offset:128
	global_load_dword v124, v39, s[82:83] offset:192
	s_waitcnt vmcnt(28)
	v_mfma_f32_16x16x4_f32 v[2:5], v85, v179, v[2:5]
	v_mfma_f32_16x16x4_f32 v[6:9], v85, v195, v[6:9]
	v_mfma_f32_16x16x4_f32 v[10:13], v85, v211, v[10:13]
	v_mfma_f32_16x16x4_f32 v[14:17], v85, v117, v[14:17]
	v_mfma_f32_16x16x4_f32 v[18:21], v101, v179, v[18:21]
	v_mfma_f32_16x16x4_f32 v[22:25], v101, v195, v[22:25]
	v_mfma_f32_16x16x4_f32 v[26:29], v101, v211, v[26:29]
	v_mfma_f32_16x16x4_f32 v[30:33], v101, v117, v[30:33]
	s_add_u32 s82, s76, 0x3c100
	s_addc_u32 s83, s77, 0
	global_load_dword v187, v39, s[82:83] offset:0
	global_load_dword v203, v39, s[82:83] offset:64
	global_load_dword v219, v39, s[82:83] offset:128
	global_load_dword v125, v39, s[82:83] offset:192
	s_waitcnt vmcnt(28)
	v_mfma_f32_16x16x4_f32 v[2:5], v86, v180, v[2:5]
	v_mfma_f32_16x16x4_f32 v[6:9], v86, v196, v[6:9]
	v_mfma_f32_16x16x4_f32 v[10:13], v86, v212, v[10:13]
	v_mfma_f32_16x16x4_f32 v[14:17], v86, v118, v[14:17]
	v_mfma_f32_16x16x4_f32 v[18:21], v102, v180, v[18:21]
	v_mfma_f32_16x16x4_f32 v[22:25], v102, v196, v[22:25]
	v_mfma_f32_16x16x4_f32 v[26:29], v102, v212, v[26:29]
	v_mfma_f32_16x16x4_f32 v[30:33], v102, v118, v[30:33]
	s_waitcnt vmcnt(24)
	v_mfma_f32_16x16x4_f32 v[2:5], v87, v181, v[2:5]
	v_mfma_f32_16x16x4_f32 v[6:9], v87, v197, v[6:9]
	v_mfma_f32_16x16x4_f32 v[10:13], v87, v213, v[10:13]
	v_mfma_f32_16x16x4_f32 v[14:17], v87, v119, v[14:17]
	v_mfma_f32_16x16x4_f32 v[18:21], v103, v181, v[18:21]
	v_mfma_f32_16x16x4_f32 v[22:25], v103, v197, v[22:25]
	v_mfma_f32_16x16x4_f32 v[26:29], v103, v213, v[26:29]
	v_mfma_f32_16x16x4_f32 v[30:33], v103, v119, v[30:33]
	s_waitcnt vmcnt(20)
	v_mfma_f32_16x16x4_f32 v[2:5], v88, v182, v[2:5]
	v_mfma_f32_16x16x4_f32 v[6:9], v88, v198, v[6:9]
	v_mfma_f32_16x16x4_f32 v[10:13], v88, v214, v[10:13]
	v_mfma_f32_16x16x4_f32 v[14:17], v88, v120, v[14:17]
	v_mfma_f32_16x16x4_f32 v[18:21], v104, v182, v[18:21]
	v_mfma_f32_16x16x4_f32 v[22:25], v104, v198, v[22:25]
	v_mfma_f32_16x16x4_f32 v[26:29], v104, v214, v[26:29]
	v_mfma_f32_16x16x4_f32 v[30:33], v104, v120, v[30:33]
	s_waitcnt vmcnt(16)
	v_mfma_f32_16x16x4_f32 v[2:5], v89, v183, v[2:5]
	v_mfma_f32_16x16x4_f32 v[6:9], v89, v199, v[6:9]
	v_mfma_f32_16x16x4_f32 v[10:13], v89, v215, v[10:13]
	v_mfma_f32_16x16x4_f32 v[14:17], v89, v121, v[14:17]
	v_mfma_f32_16x16x4_f32 v[18:21], v105, v183, v[18:21]
	v_mfma_f32_16x16x4_f32 v[22:25], v105, v199, v[22:25]
	v_mfma_f32_16x16x4_f32 v[26:29], v105, v215, v[26:29]
	v_mfma_f32_16x16x4_f32 v[30:33], v105, v121, v[30:33]
	s_waitcnt vmcnt(12)
	v_mfma_f32_16x16x4_f32 v[2:5], v90, v184, v[2:5]
	v_mfma_f32_16x16x4_f32 v[6:9], v90, v200, v[6:9]
	v_mfma_f32_16x16x4_f32 v[10:13], v90, v216, v[10:13]
	v_mfma_f32_16x16x4_f32 v[14:17], v90, v122, v[14:17]
	v_mfma_f32_16x16x4_f32 v[18:21], v106, v184, v[18:21]
	v_mfma_f32_16x16x4_f32 v[22:25], v106, v200, v[22:25]
	v_mfma_f32_16x16x4_f32 v[26:29], v106, v216, v[26:29]
	v_mfma_f32_16x16x4_f32 v[30:33], v106, v122, v[30:33]
	s_waitcnt vmcnt(8)
	v_mfma_f32_16x16x4_f32 v[2:5], v91, v185, v[2:5]
	v_mfma_f32_16x16x4_f32 v[6:9], v91, v201, v[6:9]
	v_mfma_f32_16x16x4_f32 v[10:13], v91, v217, v[10:13]
	v_mfma_f32_16x16x4_f32 v[14:17], v91, v123, v[14:17]
	v_mfma_f32_16x16x4_f32 v[18:21], v107, v185, v[18:21]
	v_mfma_f32_16x16x4_f32 v[22:25], v107, v201, v[22:25]
	v_mfma_f32_16x16x4_f32 v[26:29], v107, v217, v[26:29]
	v_mfma_f32_16x16x4_f32 v[30:33], v107, v123, v[30:33]
	s_waitcnt vmcnt(4)
	v_mfma_f32_16x16x4_f32 v[2:5], v92, v186, v[2:5]
	v_mfma_f32_16x16x4_f32 v[6:9], v92, v202, v[6:9]
	v_mfma_f32_16x16x4_f32 v[10:13], v92, v218, v[10:13]
	v_mfma_f32_16x16x4_f32 v[14:17], v92, v124, v[14:17]
	v_mfma_f32_16x16x4_f32 v[18:21], v108, v186, v[18:21]
	v_mfma_f32_16x16x4_f32 v[22:25], v108, v202, v[22:25]
	v_mfma_f32_16x16x4_f32 v[26:29], v108, v218, v[26:29]
	v_mfma_f32_16x16x4_f32 v[30:33], v108, v124, v[30:33]
	s_waitcnt vmcnt(0)
	v_mfma_f32_16x16x4_f32 v[2:5], v93, v187, v[2:5]
	v_mfma_f32_16x16x4_f32 v[6:9], v93, v203, v[6:9]
	v_mfma_f32_16x16x4_f32 v[10:13], v93, v219, v[10:13]
	v_mfma_f32_16x16x4_f32 v[14:17], v93, v125, v[14:17]
	v_mfma_f32_16x16x4_f32 v[18:21], v109, v187, v[18:21]
	v_mfma_f32_16x16x4_f32 v[22:25], v109, v203, v[22:25]
	v_mfma_f32_16x16x4_f32 v[26:29], v109, v219, v[26:29]
	v_mfma_f32_16x16x4_f32 v[30:33], v109, v125, v[30:33]
	s_nop 7
	s_nop 7
	s_nop 3
	v_mul_f32_e64 v148, |v140|, v126
	v_mul_f32_e64 v149, |v140|, v127
	v_mul_f32_e64 v150, |v140|, v128
	v_mul_f32_e64 v151, |v140|, v129
	v_mul_f32_e64 v152, |v140|, v130
	v_mul_f32_e64 v153, |v140|, v131
	v_mul_f32_e64 v154, |v140|, v132
	v_mul_f32_e64 v155, |v140|, v133
	v_mul_f32_e32 v148, 0x3fb8aa3b, v148
	v_mul_f32_e32 v149, 0x3fb8aa3b, v149
	v_mul_f32_e32 v150, 0x3fb8aa3b, v150
	v_mul_f32_e32 v151, 0x3fb8aa3b, v151
	v_mul_f32_e32 v152, 0x3fb8aa3b, v152
	v_mul_f32_e32 v153, 0x3fb8aa3b, v153
	v_mul_f32_e32 v154, 0x3fb8aa3b, v154
	v_mul_f32_e32 v155, 0x3fb8aa3b, v155
	v_exp_f32_e32 v148, v148
	v_exp_f32_e32 v149, v149
	v_exp_f32_e32 v150, v150
	v_exp_f32_e32 v151, v151
	v_exp_f32_e32 v152, v152
	v_exp_f32_e32 v153, v153
	v_exp_f32_e32 v154, v154
	v_exp_f32_e32 v155, v155
	v_mul_f32_e32 v2, v148, v2
	v_mul_f32_e32 v3, v149, v3
	v_mul_f32_e32 v4, v150, v4
	v_mul_f32_e32 v5, v151, v5
	v_mul_f32_e32 v18, v152, v18
	v_mul_f32_e32 v19, v153, v19
	v_mul_f32_e32 v20, v154, v20
	v_mul_f32_e32 v21, v155, v21
	v_mul_f32_e32 v144, v2, v2
	v_mul_f32_e32 v144, v137, v144
	v_fmac_f32_e32 v144, v3, v3
	v_fmac_f32_e32 v144, v4, v4
	v_fmac_f32_e32 v144, v5, v5
	v_fmac_f32_e32 v144, v18, v18
	v_fmac_f32_e32 v144, v19, v19
	v_fmac_f32_e32 v144, v20, v20
	v_fmac_f32_e32 v144, v21, v21
	s_add_u32 s84, s40, 0x200000
	s_addc_u32 s85, s41, 0
	global_store_dwordx4 v40, v[2:5], s[84:85]
	global_store_dwordx4 v40, v[18:21], s[84:85] offset:64
	v_mul_f32_e64 v148, |v141|, v126
	v_mul_f32_e64 v149, |v141|, v127
	v_mul_f32_e64 v150, |v141|, v128
	v_mul_f32_e64 v151, |v141|, v129
	v_mul_f32_e64 v152, |v141|, v130
	v_mul_f32_e64 v153, |v141|, v131
	v_mul_f32_e64 v154, |v141|, v132
	v_mul_f32_e64 v155, |v141|, v133
	v_mul_f32_e32 v148, 0x3fb8aa3b, v148
	v_mul_f32_e32 v149, 0x3fb8aa3b, v149
	v_mul_f32_e32 v150, 0x3fb8aa3b, v150
	v_mul_f32_e32 v151, 0x3fb8aa3b, v151
	v_mul_f32_e32 v152, 0x3fb8aa3b, v152
	v_mul_f32_e32 v153, 0x3fb8aa3b, v153
	v_mul_f32_e32 v154, 0x3fb8aa3b, v154
	v_mul_f32_e32 v155, 0x3fb8aa3b, v155
	v_exp_f32_e32 v148, v148
	v_exp_f32_e32 v149, v149
	v_exp_f32_e32 v150, v150
	v_exp_f32_e32 v151, v151
	v_exp_f32_e32 v152, v152
	v_exp_f32_e32 v153, v153
	v_exp_f32_e32 v154, v154
	v_exp_f32_e32 v155, v155
	v_mul_f32_e32 v6, v148, v6
	v_mul_f32_e32 v7, v149, v7
	v_mul_f32_e32 v8, v150, v8
	v_mul_f32_e32 v9, v151, v9
	v_mul_f32_e32 v22, v152, v22
	v_mul_f32_e32 v23, v153, v23
	v_mul_f32_e32 v24, v154, v24
	v_mul_f32_e32 v25, v155, v25
	v_mul_f32_e32 v145, v6, v6
	v_mul_f32_e32 v145, v137, v145
	v_fmac_f32_e32 v145, v7, v7
	v_fmac_f32_e32 v145, v8, v8
	v_fmac_f32_e32 v145, v9, v9
	v_fmac_f32_e32 v145, v22, v22
	v_fmac_f32_e32 v145, v23, v23
	v_fmac_f32_e32 v145, v24, v24
	v_fmac_f32_e32 v145, v25, v25
	s_add_u32 s84, s40, 0x280000
	s_addc_u32 s85, s41, 0
	global_store_dwordx4 v40, v[6:9], s[84:85]
	global_store_dwordx4 v40, v[22:25], s[84:85] offset:64
	v_mul_f32_e64 v148, |v142|, v126
	v_mul_f32_e64 v149, |v142|, v127
	v_mul_f32_e64 v150, |v142|, v128
	v_mul_f32_e64 v151, |v142|, v129
	v_mul_f32_e64 v152, |v142|, v130
	v_mul_f32_e64 v153, |v142|, v131
	v_mul_f32_e64 v154, |v142|, v132
	v_mul_f32_e64 v155, |v142|, v133
	v_mul_f32_e32 v148, 0x3fb8aa3b, v148
	v_mul_f32_e32 v149, 0x3fb8aa3b, v149
	v_mul_f32_e32 v150, 0x3fb8aa3b, v150
	v_mul_f32_e32 v151, 0x3fb8aa3b, v151
	v_mul_f32_e32 v152, 0x3fb8aa3b, v152
	v_mul_f32_e32 v153, 0x3fb8aa3b, v153
	v_mul_f32_e32 v154, 0x3fb8aa3b, v154
	v_mul_f32_e32 v155, 0x3fb8aa3b, v155
	v_exp_f32_e32 v148, v148
	v_exp_f32_e32 v149, v149
	v_exp_f32_e32 v150, v150
	v_exp_f32_e32 v151, v151
	v_exp_f32_e32 v152, v152
	v_exp_f32_e32 v153, v153
	v_exp_f32_e32 v154, v154
	v_exp_f32_e32 v155, v155
	v_mul_f32_e32 v10, v148, v10
	v_mul_f32_e32 v11, v149, v11
	v_mul_f32_e32 v12, v150, v12
	v_mul_f32_e32 v13, v151, v13
	v_mul_f32_e32 v26, v152, v26
	v_mul_f32_e32 v27, v153, v27
	v_mul_f32_e32 v28, v154, v28
	v_mul_f32_e32 v29, v155, v29
	v_mul_f32_e32 v146, v10, v10
	v_mul_f32_e32 v146, v137, v146
	v_fmac_f32_e32 v146, v11, v11
	v_fmac_f32_e32 v146, v12, v12
	v_fmac_f32_e32 v146, v13, v13
	v_fmac_f32_e32 v146, v26, v26
	v_fmac_f32_e32 v146, v27, v27
	v_fmac_f32_e32 v146, v28, v28
	v_fmac_f32_e32 v146, v29, v29
	s_add_u32 s84, s40, 0x300000
	s_addc_u32 s85, s41, 0
	global_store_dwordx4 v40, v[10:13], s[84:85]
	global_store_dwordx4 v40, v[26:29], s[84:85] offset:64
	v_mul_f32_e64 v148, |v143|, v126
	v_mul_f32_e64 v149, |v143|, v127
	v_mul_f32_e64 v150, |v143|, v128
	v_mul_f32_e64 v151, |v143|, v129
	v_mul_f32_e64 v152, |v143|, v130
	v_mul_f32_e64 v153, |v143|, v131
	v_mul_f32_e64 v154, |v143|, v132
	v_mul_f32_e64 v155, |v143|, v133
	v_mul_f32_e32 v148, 0x3fb8aa3b, v148
	v_mul_f32_e32 v149, 0x3fb8aa3b, v149
	v_mul_f32_e32 v150, 0x3fb8aa3b, v150
	v_mul_f32_e32 v151, 0x3fb8aa3b, v151
	v_mul_f32_e32 v152, 0x3fb8aa3b, v152
	v_mul_f32_e32 v153, 0x3fb8aa3b, v153
	v_mul_f32_e32 v154, 0x3fb8aa3b, v154
	v_mul_f32_e32 v155, 0x3fb8aa3b, v155
	v_exp_f32_e32 v148, v148
	v_exp_f32_e32 v149, v149
	v_exp_f32_e32 v150, v150
	v_exp_f32_e32 v151, v151
	v_exp_f32_e32 v152, v152
	v_exp_f32_e32 v153, v153
	v_exp_f32_e32 v154, v154
	v_exp_f32_e32 v155, v155
	v_mul_f32_e32 v14, v148, v14
	v_mul_f32_e32 v15, v149, v15
	v_mul_f32_e32 v16, v150, v16
	v_mul_f32_e32 v17, v151, v17
	v_mul_f32_e32 v30, v152, v30
	v_mul_f32_e32 v31, v153, v31
	v_mul_f32_e32 v32, v154, v32
	v_mul_f32_e32 v33, v155, v33
	v_mul_f32_e32 v147, v14, v14
	v_mul_f32_e32 v147, v137, v147
	v_fmac_f32_e32 v147, v15, v15
	v_fmac_f32_e32 v147, v16, v16
	v_fmac_f32_e32 v147, v17, v17
	v_fmac_f32_e32 v147, v30, v30
	v_fmac_f32_e32 v147, v31, v31
	v_fmac_f32_e32 v147, v32, v32
	v_fmac_f32_e32 v147, v33, v33
	s_add_u32 s84, s40, 0x380000
	s_addc_u32 s85, s41, 0
	global_store_dwordx4 v40, v[14:17], s[84:85]
	global_store_dwordx4 v40, v[30:33], s[84:85] offset:64
	ds_bpermute_b32 v148, v135, v144
	ds_bpermute_b32 v149, v135, v145
	ds_bpermute_b32 v150, v135, v146
	ds_bpermute_b32 v151, v135, v147
	s_waitcnt lgkmcnt(0)
	v_add_f32_e32 v144, v144, v148
	v_add_f32_e32 v145, v145, v149
	v_add_f32_e32 v146, v146, v150
	v_add_f32_e32 v147, v147, v151
	ds_bpermute_b32 v148, v136, v144
	ds_bpermute_b32 v149, v136, v145
	ds_bpermute_b32 v150, v136, v146
	ds_bpermute_b32 v151, v136, v147
	s_waitcnt lgkmcnt(0)
	v_add_f32_e32 v144, v144, v148
	v_add_f32_e32 v145, v145, v149
	v_add_f32_e32 v146, v146, v150
	v_add_f32_e32 v147, v147, v151
	global_store_dword v138, v144, s[26:27] offset:256
	global_store_dword v138, v145, s[26:27] offset:320
	global_store_dword v138, v146, s[26:27] offset:384
	global_store_dword v138, v147, s[26:27] offset:448
	s_nop 1
